# grid barrier between the batch-0 W_o phase and the batch-1 input-projection phase removed (the two phases touch disjoint rows/buffers)
# speedup vs baseline: 1.0012x; 1.0011x over previous
; #define LAS __attribute__((address_space(3)))
; __device__ __forceinline__ unsigned xb_xcc_id() { return (unsigned)__builtin_amdgcn_s_getreg((3 << 11) | 20) & 0xFu; }
; __device__ __forceinline__ int fresh_lane() { unsigned m_ = ~0u; asm volatile("" : "+s"(m_)); return (int)__builtin_amdgcn_mbcnt_hi(m_, __builtin_amdgcn_mbcnt_lo(m_, 0u)); }
; __device__ __forceinline__ const void* ldp(LAS unsigned long long* tab, int i) { const unsigned long long v = tab[i]; const unsigned lo = __builtin_amdgcn_readfirstlane((unsigned)v), hi = __builtin_amdgcn_readfirstlane((unsigned)(v >> 32)); return (const void*)(const __attribute__((address_space(1)) ...
; __global__ void __launch_bounds__(512, 2) mega(Args a) {
;     ...
;         if (ph + 1 < ph_hi) for (int prep_ = 0; prep_ < PROBE_SYNC; ++prep_) { if (ph_hi > 1000) grid.sync(); else { XcdBarrier gb_; gb_.bar = (unsigned*)ldp(tab, 30); gb_.x = xb_xcc_id(); gb_.st = (volatile LAS unsigned*)(lds + 131072 + 512); xcd_barrier(gb_, wave == 0 && fresh_lane() == 0); } }
.LBB0_1027:
	s_add_i32 s30, s30, 1
	v_readlane_b32 s0, v254, 40
	s_cmp_ge_i32 s30, s0
	v_readlane_b32 s24, v254, 25
	v_readlane_b32 s25, v254, 26
	v_readlane_b32 s26, v254, 27
	s_cbranch_scc1 .Ltramp_11
	s_cmp_eq_u32 s30, 10
	s_cbranch_scc1 .Ltramp_11
	s_cmpk_lt_i32 s0, 0x3e9
	s_mov_b64 s[0:1], -1
	s_cbranch_scc0 .LBB0_1084
	v_readlane_b32 s0, v254, 19
	s_cmp_lg_u32 s89, 0
	s_mov_b64 s[6:7], 0
	v_mov_b32_e32 v0, s0
	ds_read_b64 v[0:1], v0
	s_getreg_b32 s2, hwreg(HW_REG_XCC_ID, 0, 4)
	s_waitcnt lgkmcnt(0)
	v_readfirstlane_b32 s5, v1
	v_readfirstlane_b32 s4, v0
	s_cbranch_scc1 .LBB0_1031
	s_mov_b32 s0, -1
	s_nop 0
	v_mbcnt_lo_u32_b32 v0, s0, 0
	v_mbcnt_hi_u32_b32 v0, s0, v0
	v_cmp_eq_u32_e32 vcc, 0, v0
	s_and_b64 s[6:7], vcc, exec
